# v4: + phase-0 x->bf16 loop: batch 4 row loads, counted vmcnt(3)
# baseline (speedup 1.0000x reference)
.LBB0_91:
	s_waitcnt lgkmcnt(0)
	global_load_dwordx4 v[16:19], v[4:5], off offset:-3072
	global_load_dwordx4 v[20:23], v[4:5], off offset:-2048
	global_load_dwordx4 v[24:27], v[4:5], off offset:-1024
	global_load_dwordx4 v[28:31], v[4:5], off
	s_waitcnt vmcnt(3)
	v_cvt_pk_bf16_f32 v32, v16, v17
	v_cvt_pk_bf16_f32 v33, v18, v19
	global_store_dwordx2 v[6:7], v[32:33], off offset:-1024
	v_mul_f32_e32 v15, v17, v17
	v_mul_f32_e32 v17, v19, v19
	v_fmac_f32_e32 v15, v16, v16
	v_fmac_f32_e32 v17, v18, v18
	v_add_f32_e32 v15, v15, v17
	s_waitcnt vmcnt(3)
	v_cvt_pk_bf16_f32 v34, v20, v21
	v_cvt_pk_bf16_f32 v35, v22, v23
	global_store_dwordx2 v[6:7], v[34:35], off offset:-512
	v_mul_f32_e32 v16, v21, v21
	v_mul_f32_e32 v17, v23, v23
	v_fmac_f32_e32 v16, v20, v20
	v_fmac_f32_e32 v17, v22, v22
	v_add_f32_e32 v16, v16, v17
	v_add_f32_e32 v15, v15, v16
	s_waitcnt vmcnt(3)
	v_cvt_pk_bf16_f32 v36, v24, v25
	v_cvt_pk_bf16_f32 v37, v26, v27
	global_store_dwordx2 v[6:7], v[36:37], off
	v_mul_f32_e32 v16, v25, v25
	v_mul_f32_e32 v17, v27, v27
	v_fmac_f32_e32 v16, v24, v24
	v_fmac_f32_e32 v17, v26, v26
	v_add_f32_e32 v16, v16, v17
	v_add_f32_e32 v15, v15, v16
	s_waitcnt vmcnt(3)
	v_mul_f32_e32 v16, v29, v29
	v_mul_f32_e32 v17, v31, v31
	v_fmac_f32_e32 v16, v28, v28
	v_fmac_f32_e32 v17, v30, v30
	v_add_f32_e32 v16, v16, v17
	v_add_f32_e32 v15, v15, v16
	ds_bpermute_b32 v16, v8, v15
	v_cvt_pk_bf16_f32 v18, v28, v29
	v_cvt_pk_bf16_f32 v19, v30, v31
	global_store_dwordx2 v[6:7], v[18:19], off offset:512
	s_waitcnt lgkmcnt(0)
	v_add_f32_e32 v15, v15, v16
	ds_bpermute_b32 v16, v9, v15
	s_waitcnt lgkmcnt(0)
	v_add_f32_e32 v15, v15, v16
	ds_bpermute_b32 v16, v11, v15
	s_waitcnt lgkmcnt(0)
	v_add_f32_e32 v15, v15, v16
	ds_bpermute_b32 v16, v12, v15
	s_waitcnt lgkmcnt(0)
	v_add_f32_e32 v15, v15, v16
	ds_bpermute_b32 v16, v13, v15
	s_waitcnt lgkmcnt(0)
	v_add_f32_e32 v15, v15, v16
	ds_bpermute_b32 v16, v14, v15
	s_and_saveexec_b64 s[18:19], vcc
	s_cbranch_execz .LBB0_90
	s_waitcnt lgkmcnt(0)
	v_add_f32_e32 v15, v15, v16
	v_mul_f32_e32 v15, 0x4b800000, v15
	v_trunc_f32_e32 v15, v15
	v_mul_f32_e32 v16, 0x2f800000, v15
	v_floor_f32_e32 v16, v16
	v_fmac_f32_e32 v15, 0xcf800000, v16
	v_cvt_u32_f32_e32 v17, v16
	v_cvt_u32_f32_e32 v16, v15
	s_add_u32 s20, s0, 0xfffc0000
	s_addc_u32 s21, s1, -1
	global_store_dwordx2 v2, v[16:17], s[20:21]
	global_store_dwordx2 v2, v[2:3], s[0:1]
	s_branch .LBB0_90
